# attention softmax: row-max exchange via v_permlane16/32_swap instead of ds_bpermute
# speedup vs baseline: 1.0064x; 1.0064x over previous
; DI float fexp2(float x) { return __builtin_amdgcn_exp2f(x); }
;     ...
;                 float mx = as[0][qb][0];
; #pragma unroll
;                 for (int kb = 0; kb < 4; ++kb)
; #pragma unroll
;                     for (int rr = 0; rr < 4; ++rr) mx = fmaxf(mx, as[kb][qb][rr]);
;                 mx = fmaxf(mx, __shfl_xor(mx, 16)); mx = fmaxf(mx, __shfl_xor(mx, 32));
;                 const float mnew = fmaxf(m[qb], mx);
;                 alpha[qb] = fexp2(m[qb] - mnew); m[qb] = mnew;
;                 float ps = 0.f;
; #pragma unroll
;                 for (int kb = 0; kb < 4; ++kb)
; #pragma unroll
;                     for (int rr = 0; rr < 4; ++rr) { const float pv = fexp2(as[kb][qb][rr] - mnew); as[kb][qb][rr] = pv; ps += pv; }
;                 lsum[qb] = lsum[qb] * alpha[qb] + ps;
;             }
;             if (__builtin_amdgcn_ballot_w64(alpha[0] != 1.f || alpha[1] != 1.f) != 0ull) {
; #pragma unroll
;                 for (int d = 0; d < 8; ++d)
; #pragma unroll
;                     for (int qb = 0; qb < 2; ++qb) ao[d][qb] = ao[d][qb] * alpha[qb];
;             }
.LBB0_936:
	v_max_f32_e32 v146, v128, v128
	v_max_f32_e32 v148, v117, v117
	v_max_f32_e32 v149, v116, v116
	v_max_f32_e32 v148, v149, v148
	v_max_f32_e32 v144, v129, v129
	v_max_f32_e32 v144, v146, v144
	v_max3_f32 v144, v144, v130, v131
	v_max3_f32 v148, v148, v118, v119
	v_max3_f32 v144, v144, v124, v125
	v_max3_f32 v148, v148, v112, v113
	v_max3_f32 v144, v144, v126, v127
	v_max3_f32 v148, v148, v114, v115
	v_max3_f32 v144, v144, v132, v133
	v_max3_f32 v148, v148, v120, v121
	v_max3_f32 v144, v144, v134, v135
	v_max3_f32 v148, v148, v122, v123
	v_max3_f32 v144, v144, v140, v141
	v_max3_f32 v148, v148, v136, v137
	v_max3_f32 v144, v144, v142, v143
	v_max3_f32 v148, v148, v138, v139
	v_mov_b32_e32 v146, v144
	v_mov_b32_e32 v149, v148
	s_nop 1
	v_permlane16_swap_b32_e32 v144, v146
	v_permlane16_swap_b32_e32 v148, v149
	v_max_f32_e32 v144, v144, v146
	v_max_f32_e32 v148, v148, v149
	v_mov_b32_e32 v146, v144
	v_mov_b32_e32 v149, v148
	s_nop 1
	v_permlane32_swap_b32_e32 v144, v146
	v_permlane32_swap_b32_e32 v148, v149
	v_max3_f32 v146, v225, v144, v146
	v_max3_f32 v147, v224, v148, v149
	v_sub_f32_e32 v144, v225, v146
	v_sub_f32_e32 v145, v224, v147
	v_exp_f32_e32 v144, v144
	v_exp_f32_e32 v145, v145
	v_cmp_neq_f32_e32 vcc, 1.0, v144
	v_cmp_neq_f32_e64 s[0:1], 1.0, v145
	s_or_b64 vcc, s[0:1], vcc
	s_cbranch_vccz .LBB0_938
	v_mov_b32_e32 v148, v145
	v_pk_mul_f32 v[58:59], v[58:59], v[144:145] op_sel_hi:[1,0]
	v_pk_mul_f32 v[56:57], v[56:57], v[144:145] op_sel_hi:[1,0]
	v_pk_mul_f32 v[46:47], v[46:47], v[148:149] op_sel_hi:[1,0]
	v_pk_mul_f32 v[44:45], v[44:45], v[148:149] op_sel_hi:[1,0]
	v_pk_mul_f32 v[62:63], v[62:63], v[144:145] op_sel_hi:[1,0]
	v_pk_mul_f32 v[60:61], v[60:61], v[144:145] op_sel_hi:[1,0]
	v_pk_mul_f32 v[50:51], v[50:51], v[148:149] op_sel_hi:[1,0]
	v_pk_mul_f32 v[48:49], v[48:49], v[148:149] op_sel_hi:[1,0]
	v_pk_mul_f32 v[54:55], v[54:55], v[144:145] op_sel_hi:[1,0]
	v_pk_mul_f32 v[52:53], v[52:53], v[144:145] op_sel_hi:[1,0]
	v_pk_mul_f32 v[38:39], v[38:39], v[148:149] op_sel_hi:[1,0]
	v_pk_mul_f32 v[36:37], v[36:37], v[148:149] op_sel_hi:[1,0]
	v_pk_mul_f32 v[42:43], v[42:43], v[144:145] op_sel_hi:[1,0]
	v_pk_mul_f32 v[40:41], v[40:41], v[144:145] op_sel_hi:[1,0]
	v_pk_mul_f32 v[30:31], v[30:31], v[148:149] op_sel_hi:[1,0]
	v_pk_mul_f32 v[28:29], v[28:29], v[148:149] op_sel_hi:[1,0]
	v_pk_mul_f32 v[34:35], v[34:35], v[144:145] op_sel_hi:[1,0]
	v_pk_mul_f32 v[32:33], v[32:33], v[144:145] op_sel_hi:[1,0]
	v_pk_mul_f32 v[18:19], v[18:19], v[148:149] op_sel_hi:[1,0]
	v_pk_mul_f32 v[16:17], v[16:17], v[148:149] op_sel_hi:[1,0]
	v_pk_mul_f32 v[22:23], v[22:23], v[144:145] op_sel_hi:[1,0]
	v_pk_mul_f32 v[20:21], v[20:21], v[144:145] op_sel_hi:[1,0]
	v_pk_mul_f32 v[2:3], v[2:3], v[148:149] op_sel_hi:[1,0]
	v_pk_mul_f32 v[0:1], v[0:1], v[148:149] op_sel_hi:[1,0]
	v_pk_mul_f32 v[10:11], v[10:11], v[144:145] op_sel_hi:[1,0]
	v_pk_mul_f32 v[8:9], v[8:9], v[144:145] op_sel_hi:[1,0]
	v_pk_mul_f32 v[6:7], v[6:7], v[148:149] op_sel_hi:[1,0]
	v_pk_mul_f32 v[4:5], v[4:5], v[148:149] op_sel_hi:[1,0]
	v_pk_mul_f32 v[26:27], v[26:27], v[144:145] op_sel_hi:[1,0]
	v_pk_mul_f32 v[24:25], v[24:25], v[144:145] op_sel_hi:[1,0]
	v_pk_mul_f32 v[14:15], v[14:15], v[148:149] op_sel_hi:[1,0]
	v_pk_mul_f32 v[12:13], v[12:13], v[148:149] op_sel_hi:[1,0]
